# P1 K-loop: s_nop padding so every 8-byte instruction (MFMA, ds_read_b128, LDS-DMA) starts on an 8-byte boundary; P5/P6 loop heads pinned
# speedup vs baseline: 1.0025x; 1.0025x over previous
; #define PG8_STAGE(bufoff, gbase, voff) do { _Pragma("unroll") for (int _i = 0; _i < 2; ++_i) \
;         __builtin_amdgcn_global_load_lds((const unsigned*)((const char*)(gbase) + (voff)[_i]), (PG8_LAS unsigned*)(lds + (bufoff) + ldsw + _i * 8192), 16, 0, 0); } while (0)
; #define PG8_LDA(dst, b, h) do { _Pragma("unroll") for (int m = 0; m < 4; ++m) _Pragma("unroll") for (int k = 0; k < 2; ++k) dst[m][k] = *(const PG8_LAS bf16x8*)(lds + PG8_SA(b, h) + aoff + m * 2048 + k * 1024); } while (0)
; #define PG8_LDB(dst, b, h) do { _Pragma("unroll") for (int n = 0; n < 2; ++n) _Pragma("unroll") for (int k = 0; k < 2; ++k) dst[n][k] = *(const PG8_LAS bf16x8*)(lds + PG8_SB(b, h) + boff + n * 2048 + k * 1024); } while (0)
; #define PG8_MMA(ai, bj, At, Bt) do { __builtin_amdgcn_s_setprio(1); _Pragma("unroll") for (int m = 0; m < 4; ++m) _Pragma("unroll") for (int n = 0; n < 2; ++n) _Pragma("unroll") for (int k = 0; k < 2; ++k) \
;         acc[ai][bj][m][n] = __builtin_amdgcn_mfma_f32_16x16x32_bf16(Bt[n][k], At[m][k], acc[ai][bj][m][n], 0, 0, 0); __builtin_amdgcn_s_setprio(0); } while (0)
; #define PG8_WAIT_V(n) asm volatile("s_waitcnt vmcnt(" #n ")" ::: "memory")
; #define PG8_WAIT_L(n) asm volatile("s_waitcnt lgkmcnt(" #n ")" ::: "memory")
; #define PG8_BAR __builtin_amdgcn_s_barrier()
; #define PG8_SCHED __builtin_amdgcn_sched_barrier(0)
; template <class Epi, class Sched, bool ALIGN_EPI = false, bool SP2 = false>
; __device__ __forceinline__ void gemm_phase(PG8_LAS unsigned char* lds, const Gemm g, const Sched& S, const Epi& E) {
;     ...
;             PG8_LDB(B0, 0, 0); PG8_LDB(B1, 0, 1); PG8_SCHED; PG8_LDA(At, 0, 0); PG8_STAGE(PG8_SA(1, 1), a1 + hstep, voffA);
;             PG8_WAIT_V(8); PG8_WAIT_L(0); PG8_BAR; PG8_MMA(0, 0, At, B0); PG8_MMA(0, 1, At, B1); PG8_BAR; PG8_SCHED;
;             PG8_LDA(At, 0, 1); PG8_STAGE(PG8_SB(0, 0), b2, voffB); PG8_STAGE(PG8_SB(0, 1), b2 + hstep, voffB); PG8_STAGE(PG8_SA(0, 0), a2, voffA);
;             PG8_WAIT_V(8); PG8_WAIT_L(0); PG8_BAR; PG8_MMA(1, 0, At, B0); PG8_MMA(1, 1, At, B1); PG8_BAR; PG8_SCHED;
.LBB0_61:
	ds_read_b128 v[154:157], v151
	ds_read_b128 v[158:161], v151 offset:1024
	ds_read_b128 v[162:165], v151 offset:2048
	ds_read_b128 v[166:169], v151 offset:3072
	ds_read_b128 v[170:173], v152
	ds_read_b128 v[174:177], v152 offset:1024
	ds_read_b128 v[178:181], v152 offset:2048
	ds_read_b128 v[182:185], v152 offset:3072
	s_add_u32 s52, s54, 0xfff80080
	s_addc_u32 s53, s55, -1
	s_cmp_eq_u32 s91, 28
	s_cselect_b32 s71, s23, s53
	s_cselect_b32 s70, s87, s52
	s_cselect_b32 s69, s21, s90
	s_cselect_b32 s68, s88, s89
	s_add_i32 m0, s47, 0xc000
	ds_read_b128 v[186:189], v153
	ds_read_b128 v[190:193], v153 offset:1024
	ds_read_b128 v[194:197], v153 offset:2048
	ds_read_b128 v[198:201], v153 offset:3072
	ds_read_b128 v[202:205], v153 offset:4096
	ds_read_b128 v[206:209], v153 offset:5120
	ds_read_b128 v[210:213], v153 offset:6144
	ds_read_b128 v[214:217], v153 offset:7168
	global_load_lds_dwordx4 v138, s[54:55]
	s_add_i32 m0, s47, 0xe000
	s_nop 0
	s_nop 0
	global_load_lds_dwordx4 v140, s[54:55]
	s_waitcnt vmcnt(8)
	s_waitcnt lgkmcnt(0)
	s_barrier
	s_waitcnt lgkmcnt(0)
	v_mfma_f32_16x16x32_bf16 v[124:127], v[154:157], v[186:189], v[124:127]
	v_mfma_f32_16x16x32_bf16 v[120:123], v[162:165], v[186:189], v[120:123]
	v_mfma_f32_16x16x32_bf16 v[116:119], v[154:157], v[194:197], v[116:119]
	v_mfma_f32_16x16x32_bf16 v[108:111], v[162:165], v[194:197], v[108:111]
	v_mfma_f32_16x16x32_bf16 v[100:103], v[154:157], v[202:205], v[100:103]
	v_mfma_f32_16x16x32_bf16 v[92:95], v[162:165], v[202:205], v[92:95]
	v_mfma_f32_16x16x32_bf16 v[84:87], v[154:157], v[210:213], v[84:87]
	v_mfma_f32_16x16x32_bf16 v[76:79], v[162:165], v[210:213], v[76:79]
	v_mfma_f32_16x16x32_bf16 v[124:127], v[158:161], v[190:193], v[124:127]
	v_mfma_f32_16x16x32_bf16 v[120:123], v[166:169], v[190:193], v[120:123]
	v_mfma_f32_16x16x32_bf16 v[116:119], v[158:161], v[198:201], v[116:119]
	v_mfma_f32_16x16x32_bf16 v[108:111], v[166:169], v[198:201], v[108:111]
	v_mfma_f32_16x16x32_bf16 v[100:103], v[158:161], v[206:209], v[100:103]
	v_mfma_f32_16x16x32_bf16 v[92:95], v[166:169], v[206:209], v[92:95]
	v_mfma_f32_16x16x32_bf16 v[84:87], v[158:161], v[214:217], v[84:87]
	v_mfma_f32_16x16x32_bf16 v[76:79], v[166:169], v[214:217], v[76:79]
	v_mfma_f32_16x16x32_bf16 v[112:115], v[170:173], v[186:189], v[112:115]
	v_mfma_f32_16x16x32_bf16 v[104:107], v[178:181], v[186:189], v[104:107]
	v_mfma_f32_16x16x32_bf16 v[96:99], v[170:173], v[194:197], v[96:99]
	v_mfma_f32_16x16x32_bf16 v[88:91], v[178:181], v[194:197], v[88:91]
	v_mfma_f32_16x16x32_bf16 v[80:83], v[170:173], v[202:205], v[80:83]
	v_mfma_f32_16x16x32_bf16 v[72:75], v[178:181], v[202:205], v[72:75]
	v_mfma_f32_16x16x32_bf16 v[68:71], v[170:173], v[210:213], v[68:71]
	v_mfma_f32_16x16x32_bf16 v[64:67], v[178:181], v[210:213], v[64:67]
	v_mfma_f32_16x16x32_bf16 v[112:115], v[174:177], v[190:193], v[112:115]
	v_mfma_f32_16x16x32_bf16 v[104:107], v[182:185], v[190:193], v[104:107]
	v_mfma_f32_16x16x32_bf16 v[96:99], v[174:177], v[198:201], v[96:99]
	v_mfma_f32_16x16x32_bf16 v[88:91], v[182:185], v[198:201], v[88:91]
	v_mfma_f32_16x16x32_bf16 v[80:83], v[174:177], v[206:209], v[80:83]
	v_mfma_f32_16x16x32_bf16 v[72:75], v[182:185], v[206:209], v[72:75]
	v_mfma_f32_16x16x32_bf16 v[68:71], v[174:177], v[214:217], v[68:71]
	v_mfma_f32_16x16x32_bf16 v[64:67], v[182:185], v[214:217], v[64:67]
	s_barrier
	s_add_i32 s52, s80, s3
	s_mov_b32 m0, s52
	s_nop 0
	ds_read_b128 v[186:189], v153 offset:16384
	ds_read_b128 v[190:193], v153 offset:17408
	ds_read_b128 v[194:197], v153 offset:18432
	ds_read_b128 v[198:201], v153 offset:19456
	ds_read_b128 v[202:205], v153 offset:20480
	ds_read_b128 v[206:209], v153 offset:21504
	ds_read_b128 v[210:213], v153 offset:22528
	ds_read_b128 v[214:217], v153 offset:23552
	global_load_lds_dwordx4 v132, s[68:69]
	s_add_i32 m0, s52, 0x2000
	s_add_u32 s92, s68, 0x80000
	s_addc_u32 s93, s69, 0
	s_add_i32 s52, s81, s3
	global_load_lds_dwordx4 v128, s[68:69]
	s_mov_b32 m0, s52
	s_nop 0
	global_load_lds_dwordx4 v132, s[92:93]
	s_add_i32 m0, s52, 0x2000
	s_nop 0
	s_nop 0
	global_load_lds_dwordx4 v128, s[92:93]
	s_mov_b32 m0, s47
	s_nop 0
	global_load_lds_dwordx4 v134, s[70:71]
	s_mov_b32 m0, s73
	s_nop 0
	global_load_lds_dwordx4 v130, s[70:71]
	s_waitcnt vmcnt(8)
	s_waitcnt lgkmcnt(0)
	s_barrier
	s_waitcnt lgkmcnt(0)
	v_mfma_f32_16x16x32_bf16 v[60:63], v[154:157], v[186:189], v[60:63]
	v_mfma_f32_16x16x32_bf16 v[56:59], v[162:165], v[186:189], v[56:59]
	v_mfma_f32_16x16x32_bf16 v[52:55], v[154:157], v[194:197], v[52:55]
	v_mfma_f32_16x16x32_bf16 v[44:47], v[162:165], v[194:197], v[44:47]
	v_mfma_f32_16x16x32_bf16 v[36:39], v[154:157], v[202:205], v[36:39]
	v_mfma_f32_16x16x32_bf16 v[28:31], v[162:165], v[202:205], v[28:31]
	v_mfma_f32_16x16x32_bf16 v[20:23], v[154:157], v[210:213], v[20:23]
	v_mfma_f32_16x16x32_bf16 v[12:15], v[162:165], v[210:213], v[12:15]
	v_mfma_f32_16x16x32_bf16 v[60:63], v[158:161], v[190:193], v[60:63]
	v_mfma_f32_16x16x32_bf16 v[56:59], v[166:169], v[190:193], v[56:59]
	v_mfma_f32_16x16x32_bf16 v[52:55], v[158:161], v[198:201], v[52:55]
	v_mfma_f32_16x16x32_bf16 v[44:47], v[166:169], v[198:201], v[44:47]
	v_mfma_f32_16x16x32_bf16 v[36:39], v[158:161], v[206:209], v[36:39]
	v_mfma_f32_16x16x32_bf16 v[28:31], v[166:169], v[206:209], v[28:31]
	v_mfma_f32_16x16x32_bf16 v[20:23], v[158:161], v[214:217], v[20:23]
	v_mfma_f32_16x16x32_bf16 v[12:15], v[166:169], v[214:217], v[12:15]
	v_mfma_f32_16x16x32_bf16 v[48:51], v[170:173], v[186:189], v[48:51]
	v_mfma_f32_16x16x32_bf16 v[40:43], v[178:181], v[186:189], v[40:43]
	v_mfma_f32_16x16x32_bf16 v[32:35], v[170:173], v[194:197], v[32:35]
	v_mfma_f32_16x16x32_bf16 v[24:27], v[178:181], v[194:197], v[24:27]
	v_mfma_f32_16x16x32_bf16 v[16:19], v[170:173], v[202:205], v[16:19]
	v_mfma_f32_16x16x32_bf16 v[8:11], v[178:181], v[202:205], v[8:11]
	v_mfma_f32_16x16x32_bf16 v[4:7], v[170:173], v[210:213], v[4:7]
	v_mfma_f32_16x16x32_bf16 v[0:3], v[178:181], v[210:213], v[0:3]
	v_mfma_f32_16x16x32_bf16 v[48:51], v[174:177], v[190:193], v[48:51]
	v_mfma_f32_16x16x32_bf16 v[40:43], v[182:185], v[190:193], v[40:43]
	v_mfma_f32_16x16x32_bf16 v[32:35], v[174:177], v[198:201], v[32:35]
	v_mfma_f32_16x16x32_bf16 v[24:27], v[182:185], v[198:201], v[24:27]
	v_mfma_f32_16x16x32_bf16 v[16:19], v[174:177], v[206:209], v[16:19]
	v_mfma_f32_16x16x32_bf16 v[8:11], v[182:185], v[206:209], v[8:11]
	v_mfma_f32_16x16x32_bf16 v[4:7], v[174:177], v[214:217], v[4:7]
	v_mfma_f32_16x16x32_bf16 v[0:3], v[182:185], v[214:217], v[0:3]
	s_barrier
; #define PG8_STAGE(bufoff, gbase, voff) do { _Pragma("unroll") for (int _i = 0; _i < 2; ++_i) \
;         __builtin_amdgcn_global_load_lds((const unsigned*)((const char*)(gbase) + (voff)[_i]), (PG8_LAS unsigned*)(lds + (bufoff) + ldsw + _i * 8192), 16, 0, 0); } while (0)
; #define PG8_LDA(dst, b, h) do { _Pragma("unroll") for (int m = 0; m < 4; ++m) _Pragma("unroll") for (int k = 0; k < 2; ++k) dst[m][k] = *(const PG8_LAS bf16x8*)(lds + PG8_SA(b, h) + aoff + m * 2048 + k * 1024); } while (0)
; #define PG8_LDB(dst, b, h) do { _Pragma("unroll") for (int n = 0; n < 2; ++n) _Pragma("unroll") for (int k = 0; k < 2; ++k) dst[n][k] = *(const PG8_LAS bf16x8*)(lds + PG8_SB(b, h) + boff + n * 2048 + k * 1024); } while (0)
; #define PG8_MMA(ai, bj, At, Bt) do { __builtin_amdgcn_s_setprio(1); _Pragma("unroll") for (int m = 0; m < 4; ++m) _Pragma("unroll") for (int n = 0; n < 2; ++n) _Pragma("unroll") for (int k = 0; k < 2; ++k) \
;         acc[ai][bj][m][n] = __builtin_amdgcn_mfma_f32_16x16x32_bf16(Bt[n][k], At[m][k], acc[ai][bj][m][n], 0, 0, 0); __builtin_amdgcn_s_setprio(0); } while (0)
; #define PG8_WAIT_V(n) asm volatile("s_waitcnt vmcnt(" #n ")" ::: "memory")
; #define PG8_WAIT_L(n) asm volatile("s_waitcnt lgkmcnt(" #n ")" ::: "memory")
; #define PG8_BAR __builtin_amdgcn_s_barrier()
; #define PG8_SCHED __builtin_amdgcn_sched_barrier(0)
; template <class Epi, class Sched, bool ALIGN_EPI = false, bool SP2 = false>
; __device__ __forceinline__ void gemm_phase(PG8_LAS unsigned char* lds, const Gemm g, const Sched& S, const Epi& E) {
;     ...
;             PG8_LDB(B0, 1, 0); PG8_LDB(B1, 1, 1); PG8_SCHED; PG8_LDA(At, 1, 0); PG8_STAGE(PG8_SA(0, 1), a2 + hstep, voffA);
;             PG8_WAIT_V(8); PG8_WAIT_L(0); PG8_BAR; PG8_MMA(0, 0, At, B0); PG8_MMA(0, 1, At, B1); PG8_BAR; PG8_SCHED;
;             PG8_LDA(At, 1, 1); PG8_STAGE(PG8_SB(1, 0), b3, voffB); PG8_STAGE(PG8_SB(1, 1), b3 + hstep, voffB); PG8_STAGE(PG8_SA(1, 0), a3, voffA);
;             PG8_WAIT_V(8); PG8_WAIT_L(0); PG8_BAR; PG8_MMA(1, 0, At, B0); PG8_MMA(1, 1, At, B1); PG8_BAR; PG8_SCHED;
	s_nop 0
	s_add_i32 s52, 0, 0x18000
	v_add_u32_e32 v136, s52, v149
	s_nop 0
	s_add_i32 s53, 0, 0x1c000
	ds_read_b128 v[154:157], v136
	ds_read_b128 v[158:161], v136 offset:1024
	ds_read_b128 v[162:165], v136 offset:2048
	ds_read_b128 v[166:169], v136 offset:3072
	v_add_u32_e32 v136, s53, v149
	s_nop 0
	ds_read_b128 v[170:173], v136
	ds_read_b128 v[174:177], v136 offset:1024
	ds_read_b128 v[178:181], v136 offset:2048
	ds_read_b128 v[182:185], v136 offset:3072
	s_add_u32 s70, s70, 0x80000
	s_addc_u32 s71, s71, 0
	s_mov_b32 m0, s74
	ds_read_b128 v[186:189], v153 offset:32768
	ds_read_b128 v[190:193], v153 offset:33792
	ds_read_b128 v[194:197], v153 offset:34816
	ds_read_b128 v[198:201], v153 offset:35840
	ds_read_b128 v[202:205], v153 offset:36864
	ds_read_b128 v[206:209], v153 offset:37888
	ds_read_b128 v[210:213], v153 offset:38912
	ds_read_b128 v[214:217], v153 offset:39936
	global_load_lds_dwordx4 v134, s[70:71]
	s_mov_b32 m0, s75
	s_nop 0
	global_load_lds_dwordx4 v130, s[70:71]
	s_waitcnt vmcnt(8)
	s_waitcnt lgkmcnt(0)
	s_barrier
	s_waitcnt lgkmcnt(0)
	v_mfma_f32_16x16x32_bf16 v[124:127], v[154:157], v[186:189], v[124:127]
	v_mfma_f32_16x16x32_bf16 v[120:123], v[162:165], v[186:189], v[120:123]
	v_mfma_f32_16x16x32_bf16 v[116:119], v[154:157], v[194:197], v[116:119]
	v_mfma_f32_16x16x32_bf16 v[108:111], v[162:165], v[194:197], v[108:111]
	v_mfma_f32_16x16x32_bf16 v[100:103], v[154:157], v[202:205], v[100:103]
	v_mfma_f32_16x16x32_bf16 v[92:95], v[162:165], v[202:205], v[92:95]
	v_mfma_f32_16x16x32_bf16 v[84:87], v[154:157], v[210:213], v[84:87]
	v_mfma_f32_16x16x32_bf16 v[76:79], v[162:165], v[210:213], v[76:79]
	v_mfma_f32_16x16x32_bf16 v[124:127], v[158:161], v[190:193], v[124:127]
	v_mfma_f32_16x16x32_bf16 v[120:123], v[166:169], v[190:193], v[120:123]
	v_mfma_f32_16x16x32_bf16 v[116:119], v[158:161], v[198:201], v[116:119]
	v_mfma_f32_16x16x32_bf16 v[108:111], v[166:169], v[198:201], v[108:111]
	v_mfma_f32_16x16x32_bf16 v[100:103], v[158:161], v[206:209], v[100:103]
	v_mfma_f32_16x16x32_bf16 v[92:95], v[166:169], v[206:209], v[92:95]
	v_mfma_f32_16x16x32_bf16 v[84:87], v[158:161], v[214:217], v[84:87]
	v_mfma_f32_16x16x32_bf16 v[76:79], v[166:169], v[214:217], v[76:79]
	v_mfma_f32_16x16x32_bf16 v[112:115], v[170:173], v[186:189], v[112:115]
	v_mfma_f32_16x16x32_bf16 v[104:107], v[178:181], v[186:189], v[104:107]
	v_mfma_f32_16x16x32_bf16 v[96:99], v[170:173], v[194:197], v[96:99]
	v_mfma_f32_16x16x32_bf16 v[88:91], v[178:181], v[194:197], v[88:91]
	v_mfma_f32_16x16x32_bf16 v[80:83], v[170:173], v[202:205], v[80:83]
	v_mfma_f32_16x16x32_bf16 v[72:75], v[178:181], v[202:205], v[72:75]
	v_mfma_f32_16x16x32_bf16 v[68:71], v[170:173], v[210:213], v[68:71]
	v_mfma_f32_16x16x32_bf16 v[64:67], v[178:181], v[210:213], v[64:67]
	v_mfma_f32_16x16x32_bf16 v[112:115], v[174:177], v[190:193], v[112:115]
	v_mfma_f32_16x16x32_bf16 v[104:107], v[182:185], v[190:193], v[104:107]
	v_mfma_f32_16x16x32_bf16 v[96:99], v[174:177], v[198:201], v[96:99]
	v_mfma_f32_16x16x32_bf16 v[88:91], v[182:185], v[198:201], v[88:91]
	v_mfma_f32_16x16x32_bf16 v[80:83], v[174:177], v[206:209], v[80:83]
	v_mfma_f32_16x16x32_bf16 v[72:75], v[182:185], v[206:209], v[72:75]
	v_mfma_f32_16x16x32_bf16 v[68:71], v[174:177], v[214:217], v[68:71]
	v_mfma_f32_16x16x32_bf16 v[64:67], v[182:185], v[214:217], v[64:67]
	s_barrier
	s_add_i32 s52, s52, s3
	s_mov_b32 m0, s52
	s_nop 0
	ds_read_b128 v[186:189], v153 offset:49152
	ds_read_b128 v[190:193], v153 offset:50176
	ds_read_b128 v[194:197], v153 offset:51200
	ds_read_b128 v[198:201], v153 offset:52224
	ds_read_b128 v[202:205], v153 offset:53248
	ds_read_b128 v[206:209], v153 offset:54272
	ds_read_b128 v[210:213], v153 offset:55296
	ds_read_b128 v[214:217], v153 offset:56320
	s_add_u32 s98, s68, 0x80
	s_addc_u32 s99, s69, 0
	s_nop 0
	global_load_lds_dwordx4 v132, s[98:99]
	s_add_i32 m0, s52, 0x2000
	s_add_u32 s68, s68, 0x80080
	s_addc_u32 s69, s69, 0
	s_add_i32 s52, s53, s3
	global_load_lds_dwordx4 v128, s[98:99]
	s_mov_b32 m0, s52
	s_nop 0
	global_load_lds_dwordx4 v132, s[68:69]
	s_add_i32 m0, s52, 0x2000
	s_nop 0
	s_nop 0
	global_load_lds_dwordx4 v128, s[68:69]
	s_mov_b32 m0, s77
	s_nop 0
	s_add_u32 s100, s70, 0xfff80080
	s_addc_u32 s101, s71, -1
	s_nop 0
	global_load_lds_dwordx4 v134, s[100:101]
	s_mov_b32 m0, s78
	s_nop 0
	global_load_lds_dwordx4 v130, s[100:101]
	s_waitcnt vmcnt(8)
	s_waitcnt lgkmcnt(0)
	s_barrier
	s_waitcnt lgkmcnt(0)
	v_mfma_f32_16x16x32_bf16 v[60:63], v[154:157], v[186:189], v[60:63]
	v_mfma_f32_16x16x32_bf16 v[56:59], v[162:165], v[186:189], v[56:59]
	v_mfma_f32_16x16x32_bf16 v[52:55], v[154:157], v[194:197], v[52:55]
	v_mfma_f32_16x16x32_bf16 v[44:47], v[162:165], v[194:197], v[44:47]
	v_mfma_f32_16x16x32_bf16 v[36:39], v[154:157], v[202:205], v[36:39]
	v_mfma_f32_16x16x32_bf16 v[28:31], v[162:165], v[202:205], v[28:31]
	v_mfma_f32_16x16x32_bf16 v[20:23], v[154:157], v[210:213], v[20:23]
	v_mfma_f32_16x16x32_bf16 v[12:15], v[162:165], v[210:213], v[12:15]
	v_mfma_f32_16x16x32_bf16 v[60:63], v[158:161], v[190:193], v[60:63]
	v_mfma_f32_16x16x32_bf16 v[56:59], v[166:169], v[190:193], v[56:59]
	v_mfma_f32_16x16x32_bf16 v[52:55], v[158:161], v[198:201], v[52:55]
	v_mfma_f32_16x16x32_bf16 v[44:47], v[166:169], v[198:201], v[44:47]
	v_mfma_f32_16x16x32_bf16 v[36:39], v[158:161], v[206:209], v[36:39]
	v_mfma_f32_16x16x32_bf16 v[28:31], v[166:169], v[206:209], v[28:31]
	v_mfma_f32_16x16x32_bf16 v[20:23], v[158:161], v[214:217], v[20:23]
	v_mfma_f32_16x16x32_bf16 v[12:15], v[166:169], v[214:217], v[12:15]
	v_mfma_f32_16x16x32_bf16 v[48:51], v[170:173], v[186:189], v[48:51]
	v_mfma_f32_16x16x32_bf16 v[40:43], v[178:181], v[186:189], v[40:43]
	v_mfma_f32_16x16x32_bf16 v[32:35], v[170:173], v[194:197], v[32:35]
	v_mfma_f32_16x16x32_bf16 v[24:27], v[178:181], v[194:197], v[24:27]
	v_mfma_f32_16x16x32_bf16 v[16:19], v[170:173], v[202:205], v[16:19]
	v_mfma_f32_16x16x32_bf16 v[8:11], v[178:181], v[202:205], v[8:11]
	v_mfma_f32_16x16x32_bf16 v[4:7], v[170:173], v[210:213], v[4:7]
	v_mfma_f32_16x16x32_bf16 v[0:3], v[178:181], v[210:213], v[0:3]
	v_mfma_f32_16x16x32_bf16 v[48:51], v[174:177], v[190:193], v[48:51]
	v_mfma_f32_16x16x32_bf16 v[40:43], v[182:185], v[190:193], v[40:43]
	v_mfma_f32_16x16x32_bf16 v[32:35], v[174:177], v[198:201], v[32:35]
	v_mfma_f32_16x16x32_bf16 v[24:27], v[182:185], v[198:201], v[24:27]
	v_mfma_f32_16x16x32_bf16 v[16:19], v[174:177], v[206:209], v[16:19]
	v_mfma_f32_16x16x32_bf16 v[8:11], v[182:185], v[206:209], v[8:11]
	v_mfma_f32_16x16x32_bf16 v[4:7], v[174:177], v[214:217], v[4:7]
	v_mfma_f32_16x16x32_bf16 v[0:3], v[182:185], v[214:217], v[0:3]
	s_barrier
	s_add_i32 s91, s91, 2
	s_add_u32 s54, s54, 0x100
	s_addc_u32 s55, s55, 0
	s_nop 0
	s_add_u32 s89, s89, 0x100
	s_addc_u32 s90, s90, 0
	s_cmp_gt_u32 s91, 29
	s_cbranch_scc0 .LBB0_61
	s_and_b64 vcc, exec, s[10:11]
	s_cbranch_vccz .LBB0_64
	s_barrier
